# static s_setprio 1 for waves 4-7 at phase start, per-segment setprio toggles in both GEMM loops removed
# baseline (speedup 1.0000x reference)
.LBB0_348:
	s_add_i32 s12, s12, s11
	s_add_u32 s11, s44, s12
	s_addc_u32 s12, s45, 0
	s_add_u32 s10, s42, s10
	s_addc_u32 s13, s43, 0
	s_add_u32 s10, s10, 0x100
	s_addc_u32 s13, s13, 0
	s_add_i32 s14, 0, 0x10000
	s_and_b64 s[0:1], exec, s[0:1]
	v_add_u32_e32 v155, s14, v152
	s_cselect_b32 s1, s6, s13
	s_cselect_b32 s0, s7, s10
	s_add_i32 s13, 0, 0x14000
	ds_read_b128 v[140:143], v155
	ds_read_b128 v[148:151], v155 offset:1024
	ds_read_b128 v[156:159], v155 offset:2048
	ds_read_b128 v[160:163], v155 offset:3072
	v_add_u32_e32 v155, s13, v152
	ds_read_b128 v[164:167], v155
	ds_read_b128 v[168:171], v155 offset:1024
	ds_read_b128 v[172:175], v155 offset:2048
	ds_read_b128 v[176:179], v155 offset:3072
	s_add_u32 s10, s11, 0x140080
	s_addc_u32 s11, s12, 0
	v_lshl_add_u64 v[212:213], s[10:11], 0, v[146:147]
	s_add_i32 m0, s53, 0xc000
	ds_read_b128 v[180:183], v154
	ds_read_b128 v[184:187], v154 offset:1024
	ds_read_b128 v[188:191], v154 offset:2048
	ds_read_b128 v[192:195], v154 offset:3072
	ds_read_b128 v[196:199], v154 offset:4096
	ds_read_b128 v[200:203], v154 offset:5120
	ds_read_b128 v[204:207], v154 offset:6144
	ds_read_b128 v[208:211], v154 offset:7168
	global_load_lds_dwordx4 v[212:213], off
	v_lshl_add_u64 v[212:213], s[10:11], 0, v[136:137]
	s_add_i32 m0, s53, 0xe000
	s_nop 0
	global_load_lds_dwordx4 v[212:213], off
	s_waitcnt vmcnt(8)
	s_waitcnt lgkmcnt(0)
	s_barrier
	s_waitcnt lgkmcnt(0)
	v_mfma_f32_16x16x32_bf16 v[122:125], v[140:143], v[180:183], v[122:125]
	v_mfma_f32_16x16x32_bf16 v[114:117], v[156:159], v[180:183], v[114:117]
	v_mfma_f32_16x16x32_bf16 v[102:105], v[140:143], v[188:191], v[102:105]
	v_mfma_f32_16x16x32_bf16 v[78:81], v[156:159], v[188:191], v[78:81]
	v_mfma_f32_16x16x32_bf16 v[70:73], v[140:143], v[196:199], v[70:73]
	v_mfma_f32_16x16x32_bf16 v[50:53], v[156:159], v[196:199], v[50:53]
	v_mfma_f32_16x16x32_bf16 v[42:45], v[140:143], v[204:207], v[42:45]
	v_mfma_f32_16x16x32_bf16 v[26:29], v[156:159], v[204:207], v[26:29]
	v_mfma_f32_16x16x32_bf16 v[122:125], v[148:151], v[184:187], v[122:125]
	v_mfma_f32_16x16x32_bf16 v[114:117], v[160:163], v[184:187], v[114:117]
	v_mfma_f32_16x16x32_bf16 v[102:105], v[148:151], v[192:195], v[102:105]
	v_mfma_f32_16x16x32_bf16 v[78:81], v[160:163], v[192:195], v[78:81]
	v_mfma_f32_16x16x32_bf16 v[70:73], v[148:151], v[200:203], v[70:73]
	v_mfma_f32_16x16x32_bf16 v[50:53], v[160:163], v[200:203], v[50:53]
	v_mfma_f32_16x16x32_bf16 v[42:45], v[148:151], v[208:211], v[42:45]
	v_mfma_f32_16x16x32_bf16 v[26:29], v[160:163], v[208:211], v[26:29]
	v_mfma_f32_16x16x32_bf16 v[126:129], v[164:167], v[180:183], v[126:129]
	v_mfma_f32_16x16x32_bf16 v[130:133], v[172:175], v[180:183], v[130:133]
	v_mfma_f32_16x16x32_bf16 v[110:113], v[164:167], v[188:191], v[110:113]
	v_mfma_f32_16x16x32_bf16 v[118:121], v[172:175], v[188:191], v[118:121]
	v_mfma_f32_16x16x32_bf16 v[86:89], v[164:167], v[196:199], v[86:89]
	v_mfma_f32_16x16x32_bf16 v[90:93], v[172:175], v[196:199], v[90:93]
	v_mfma_f32_16x16x32_bf16 v[58:61], v[164:167], v[204:207], v[58:61]
	v_mfma_f32_16x16x32_bf16 v[94:97], v[172:175], v[204:207], v[94:97]
	v_mfma_f32_16x16x32_bf16 v[126:129], v[168:171], v[184:187], v[126:129]
	v_mfma_f32_16x16x32_bf16 v[130:133], v[176:179], v[184:187], v[130:133]
	v_mfma_f32_16x16x32_bf16 v[110:113], v[168:171], v[192:195], v[110:113]
	v_mfma_f32_16x16x32_bf16 v[118:121], v[176:179], v[192:195], v[118:121]
	v_mfma_f32_16x16x32_bf16 v[86:89], v[168:171], v[200:203], v[86:89]
	v_mfma_f32_16x16x32_bf16 v[90:93], v[176:179], v[200:203], v[90:93]
	v_mfma_f32_16x16x32_bf16 v[58:61], v[168:171], v[208:211], v[58:61]
	v_mfma_f32_16x16x32_bf16 v[94:97], v[176:179], v[208:211], v[94:97]
	s_barrier
	s_add_i32 s10, s14, s52
	v_lshl_add_u64 v[212:213], s[0:1], 0, v[138:139]
	s_mov_b32 m0, s10
	ds_read_b128 v[180:183], v154 offset:16384
	ds_read_b128 v[184:187], v154 offset:17408
	ds_read_b128 v[188:191], v154 offset:18432
	ds_read_b128 v[192:195], v154 offset:19456
	ds_read_b128 v[196:199], v154 offset:20480
	ds_read_b128 v[200:203], v154 offset:21504
	ds_read_b128 v[204:207], v154 offset:22528
	ds_read_b128 v[208:211], v154 offset:23552
	global_load_lds_dwordx4 v[212:213], off
	s_add_i32 m0, s10, 0x2000
	s_add_u32 s10, s0, 0x80000
	v_lshl_add_u64 v[214:215], s[0:1], 0, v[134:135]
	s_addc_u32 s11, s1, 0
	s_add_i32 s12, s13, s52
	global_load_lds_dwordx4 v[214:215], off
	v_lshl_add_u64 v[216:217], s[10:11], 0, v[138:139]
	s_mov_b32 m0, s12
	v_lshl_add_u64 v[218:219], s[46:47], 0, v[136:137]
	global_load_lds_dwordx4 v[216:217], off
	v_lshl_add_u64 v[216:217], s[10:11], 0, v[134:135]
	s_add_i32 m0, s12, 0x2000
	s_nop 0
	global_load_lds_dwordx4 v[216:217], off
	v_lshl_add_u64 v[216:217], s[46:47], 0, v[146:147]
	s_mov_b32 m0, s53
	s_nop 0
	global_load_lds_dwordx4 v[216:217], off
	s_mov_b32 m0, s54
	s_nop 0
	global_load_lds_dwordx4 v[218:219], off
	s_waitcnt vmcnt(8)
	s_waitcnt lgkmcnt(0)
	s_barrier
	s_waitcnt lgkmcnt(0)
	v_mfma_f32_16x16x32_bf16 v[82:85], v[140:143], v[180:183], v[82:85]
	v_mfma_f32_16x16x32_bf16 v[62:65], v[156:159], v[180:183], v[62:65]
	v_mfma_f32_16x16x32_bf16 v[54:57], v[140:143], v[188:191], v[54:57]
	v_mfma_f32_16x16x32_bf16 v[34:37], v[156:159], v[188:191], v[34:37]
	v_mfma_f32_16x16x32_bf16 v[30:33], v[140:143], v[196:199], v[30:33]
	v_mfma_f32_16x16x32_bf16 v[14:17], v[156:159], v[196:199], v[14:17]
	v_mfma_f32_16x16x32_bf16 v[10:13], v[140:143], v[204:207], v[10:13]
	v_mfma_f32_16x16x32_bf16 v[6:9], v[156:159], v[204:207], v[6:9]
	v_mfma_f32_16x16x32_bf16 v[82:85], v[148:151], v[184:187], v[82:85]
	v_mfma_f32_16x16x32_bf16 v[62:65], v[160:163], v[184:187], v[62:65]
	v_mfma_f32_16x16x32_bf16 v[54:57], v[148:151], v[192:195], v[54:57]
	v_mfma_f32_16x16x32_bf16 v[34:37], v[160:163], v[192:195], v[34:37]
	v_mfma_f32_16x16x32_bf16 v[30:33], v[148:151], v[200:203], v[30:33]
	v_mfma_f32_16x16x32_bf16 v[14:17], v[160:163], v[200:203], v[14:17]
	v_mfma_f32_16x16x32_bf16 v[10:13], v[148:151], v[208:211], v[10:13]
	v_mfma_f32_16x16x32_bf16 v[6:9], v[160:163], v[208:211], v[6:9]
	v_mfma_f32_16x16x32_bf16 v[98:101], v[164:167], v[180:183], v[98:101]
	v_mfma_f32_16x16x32_bf16 v[106:109], v[172:175], v[180:183], v[106:109]
	v_mfma_f32_16x16x32_bf16 v[66:69], v[164:167], v[188:191], v[66:69]
	v_mfma_f32_16x16x32_bf16 v[74:77], v[172:175], v[188:191], v[74:77]
	v_mfma_f32_16x16x32_bf16 v[38:41], v[164:167], v[196:199], v[38:41]
	v_mfma_f32_16x16x32_bf16 v[46:49], v[172:175], v[196:199], v[46:49]
	v_mfma_f32_16x16x32_bf16 v[18:21], v[164:167], v[204:207], v[18:21]
	v_mfma_f32_16x16x32_bf16 v[22:25], v[172:175], v[204:207], v[22:25]
	v_mfma_f32_16x16x32_bf16 v[98:101], v[168:171], v[184:187], v[98:101]
	v_mfma_f32_16x16x32_bf16 v[106:109], v[176:179], v[184:187], v[106:109]
	v_mfma_f32_16x16x32_bf16 v[66:69], v[168:171], v[192:195], v[66:69]
	v_mfma_f32_16x16x32_bf16 v[74:77], v[176:179], v[192:195], v[74:77]
	v_mfma_f32_16x16x32_bf16 v[38:41], v[168:171], v[200:203], v[38:41]
	v_mfma_f32_16x16x32_bf16 v[46:49], v[176:179], v[200:203], v[46:49]
	v_mfma_f32_16x16x32_bf16 v[18:21], v[168:171], v[208:211], v[18:21]
	v_mfma_f32_16x16x32_bf16 v[22:25], v[176:179], v[208:211], v[22:25]
	s_barrier
	s_add_i32 s12, 0, 0x18000
	v_add_u32_e32 v155, s12, v152
	s_add_i32 s13, 0, 0x1c000
	ds_read_b128 v[140:143], v155
	ds_read_b128 v[148:151], v155 offset:1024
	ds_read_b128 v[156:159], v155 offset:2048
	ds_read_b128 v[160:163], v155 offset:3072
	v_add_u32_e32 v155, s13, v152
	ds_read_b128 v[164:167], v155
	ds_read_b128 v[168:171], v155 offset:1024
	ds_read_b128 v[172:175], v155 offset:2048
	ds_read_b128 v[176:179], v155 offset:3072
	s_add_u32 s10, s46, 0x140000
	s_addc_u32 s11, s47, 0
	s_mov_b32 m0, s55
	v_lshl_add_u64 v[220:221], s[10:11], 0, v[146:147]
	ds_read_b128 v[180:183], v154 offset:32768
	ds_read_b128 v[184:187], v154 offset:33792
	ds_read_b128 v[188:191], v154 offset:34816
	ds_read_b128 v[192:195], v154 offset:35840
	ds_read_b128 v[196:199], v154 offset:36864
	ds_read_b128 v[200:203], v154 offset:37888
	ds_read_b128 v[204:207], v154 offset:38912
	ds_read_b128 v[208:211], v154 offset:39936
	global_load_lds_dwordx4 v[220:221], off
	v_lshl_add_u64 v[220:221], s[10:11], 0, v[136:137]
	s_mov_b32 m0, s56
	s_nop 0
	global_load_lds_dwordx4 v[220:221], off
	s_waitcnt vmcnt(8)
	s_waitcnt lgkmcnt(0)
	s_barrier
	s_waitcnt lgkmcnt(0)
	v_mfma_f32_16x16x32_bf16 v[122:125], v[140:143], v[180:183], v[122:125]
	v_mfma_f32_16x16x32_bf16 v[114:117], v[156:159], v[180:183], v[114:117]
	v_mfma_f32_16x16x32_bf16 v[102:105], v[140:143], v[188:191], v[102:105]
	v_mfma_f32_16x16x32_bf16 v[78:81], v[156:159], v[188:191], v[78:81]
	v_mfma_f32_16x16x32_bf16 v[70:73], v[140:143], v[196:199], v[70:73]
	v_mfma_f32_16x16x32_bf16 v[50:53], v[156:159], v[196:199], v[50:53]
	v_mfma_f32_16x16x32_bf16 v[42:45], v[140:143], v[204:207], v[42:45]
	v_mfma_f32_16x16x32_bf16 v[26:29], v[156:159], v[204:207], v[26:29]
	v_mfma_f32_16x16x32_bf16 v[122:125], v[148:151], v[184:187], v[122:125]
	v_mfma_f32_16x16x32_bf16 v[114:117], v[160:163], v[184:187], v[114:117]
	v_mfma_f32_16x16x32_bf16 v[102:105], v[148:151], v[192:195], v[102:105]
	v_mfma_f32_16x16x32_bf16 v[78:81], v[160:163], v[192:195], v[78:81]
	v_mfma_f32_16x16x32_bf16 v[70:73], v[148:151], v[200:203], v[70:73]
	v_mfma_f32_16x16x32_bf16 v[50:53], v[160:163], v[200:203], v[50:53]
	v_mfma_f32_16x16x32_bf16 v[42:45], v[148:151], v[208:211], v[42:45]
	v_mfma_f32_16x16x32_bf16 v[26:29], v[160:163], v[208:211], v[26:29]
	v_mfma_f32_16x16x32_bf16 v[126:129], v[164:167], v[180:183], v[126:129]
	v_mfma_f32_16x16x32_bf16 v[130:133], v[172:175], v[180:183], v[130:133]
	v_mfma_f32_16x16x32_bf16 v[110:113], v[164:167], v[188:191], v[110:113]
	v_mfma_f32_16x16x32_bf16 v[118:121], v[172:175], v[188:191], v[118:121]
	v_mfma_f32_16x16x32_bf16 v[86:89], v[164:167], v[196:199], v[86:89]
	v_mfma_f32_16x16x32_bf16 v[90:93], v[172:175], v[196:199], v[90:93]
	v_mfma_f32_16x16x32_bf16 v[58:61], v[164:167], v[204:207], v[58:61]
	v_mfma_f32_16x16x32_bf16 v[94:97], v[172:175], v[204:207], v[94:97]
	v_mfma_f32_16x16x32_bf16 v[126:129], v[168:171], v[184:187], v[126:129]
	v_mfma_f32_16x16x32_bf16 v[130:133], v[176:179], v[184:187], v[130:133]
	v_mfma_f32_16x16x32_bf16 v[110:113], v[168:171], v[192:195], v[110:113]
	v_mfma_f32_16x16x32_bf16 v[118:121], v[176:179], v[192:195], v[118:121]
	v_mfma_f32_16x16x32_bf16 v[86:89], v[168:171], v[200:203], v[86:89]
	v_mfma_f32_16x16x32_bf16 v[90:93], v[176:179], v[200:203], v[90:93]
	v_mfma_f32_16x16x32_bf16 v[58:61], v[168:171], v[208:211], v[58:61]
	v_mfma_f32_16x16x32_bf16 v[94:97], v[176:179], v[208:211], v[94:97]
	s_barrier
	s_mov_b64 s[14:15], 0x80
	s_add_i32 s10, s12, s52
	v_lshl_add_u64 v[212:213], v[212:213], 0, s[14:15]
	s_mov_b32 m0, s10
	ds_read_b128 v[180:183], v154 offset:49152
	ds_read_b128 v[184:187], v154 offset:50176
	ds_read_b128 v[188:191], v154 offset:51200
	ds_read_b128 v[192:195], v154 offset:52224
	ds_read_b128 v[196:199], v154 offset:53248
	ds_read_b128 v[200:203], v154 offset:54272
	ds_read_b128 v[204:207], v154 offset:55296
	ds_read_b128 v[208:211], v154 offset:56320
	global_load_lds_dwordx4 v[212:213], off
	s_add_i32 m0, s10, 0x2000
	s_add_u32 s0, s0, 0x80080
	v_lshl_add_u64 v[212:213], v[214:215], 0, s[14:15]
	s_addc_u32 s1, s1, 0
	s_add_i32 s10, s13, s52
	global_load_lds_dwordx4 v[212:213], off
	v_lshl_add_u64 v[212:213], s[0:1], 0, v[138:139]
	s_mov_b32 m0, s10
	s_nop 0
	global_load_lds_dwordx4 v[212:213], off
	v_lshl_add_u64 v[212:213], s[0:1], 0, v[134:135]
	s_add_i32 m0, s10, 0x2000
	s_nop 0
	global_load_lds_dwordx4 v[212:213], off
	v_lshl_add_u64 v[212:213], v[216:217], 0, s[14:15]
	s_mov_b32 m0, s57
	s_nop 0
	global_load_lds_dwordx4 v[212:213], off
	v_lshl_add_u64 v[212:213], v[218:219], 0, s[14:15]
	s_mov_b32 m0, s58
	s_nop 0
	global_load_lds_dwordx4 v[212:213], off
	s_waitcnt vmcnt(8)
	s_waitcnt lgkmcnt(0)
	s_barrier
	s_waitcnt lgkmcnt(0)
	v_mfma_f32_16x16x32_bf16 v[82:85], v[140:143], v[180:183], v[82:85]
	v_mfma_f32_16x16x32_bf16 v[62:65], v[156:159], v[180:183], v[62:65]
	v_mfma_f32_16x16x32_bf16 v[54:57], v[140:143], v[188:191], v[54:57]
	v_mfma_f32_16x16x32_bf16 v[34:37], v[156:159], v[188:191], v[34:37]
	v_mfma_f32_16x16x32_bf16 v[30:33], v[140:143], v[196:199], v[30:33]
	v_mfma_f32_16x16x32_bf16 v[14:17], v[156:159], v[196:199], v[14:17]
	v_mfma_f32_16x16x32_bf16 v[10:13], v[140:143], v[204:207], v[10:13]
	v_mfma_f32_16x16x32_bf16 v[6:9], v[156:159], v[204:207], v[6:9]
	v_mfma_f32_16x16x32_bf16 v[82:85], v[148:151], v[184:187], v[82:85]
	v_mfma_f32_16x16x32_bf16 v[62:65], v[160:163], v[184:187], v[62:65]
	v_mfma_f32_16x16x32_bf16 v[54:57], v[148:151], v[192:195], v[54:57]
	v_mfma_f32_16x16x32_bf16 v[34:37], v[160:163], v[192:195], v[34:37]
	v_mfma_f32_16x16x32_bf16 v[30:33], v[148:151], v[200:203], v[30:33]
	v_mfma_f32_16x16x32_bf16 v[14:17], v[160:163], v[200:203], v[14:17]
	v_mfma_f32_16x16x32_bf16 v[10:13], v[148:151], v[208:211], v[10:13]
	v_mfma_f32_16x16x32_bf16 v[6:9], v[160:163], v[208:211], v[6:9]
	v_mfma_f32_16x16x32_bf16 v[98:101], v[164:167], v[180:183], v[98:101]
	v_mfma_f32_16x16x32_bf16 v[106:109], v[172:175], v[180:183], v[106:109]
	v_mfma_f32_16x16x32_bf16 v[66:69], v[164:167], v[188:191], v[66:69]
	v_mfma_f32_16x16x32_bf16 v[74:77], v[172:175], v[188:191], v[74:77]
	v_mfma_f32_16x16x32_bf16 v[38:41], v[164:167], v[196:199], v[38:41]
	v_mfma_f32_16x16x32_bf16 v[46:49], v[172:175], v[196:199], v[46:49]
	v_mfma_f32_16x16x32_bf16 v[18:21], v[164:167], v[204:207], v[18:21]
	v_mfma_f32_16x16x32_bf16 v[22:25], v[172:175], v[204:207], v[22:25]
	v_mfma_f32_16x16x32_bf16 v[98:101], v[168:171], v[184:187], v[98:101]
	v_mfma_f32_16x16x32_bf16 v[106:109], v[176:179], v[184:187], v[106:109]
	v_mfma_f32_16x16x32_bf16 v[66:69], v[168:171], v[192:195], v[66:69]
	v_mfma_f32_16x16x32_bf16 v[74:77], v[176:179], v[192:195], v[74:77]
	v_mfma_f32_16x16x32_bf16 v[38:41], v[168:171], v[200:203], v[38:41]
	v_mfma_f32_16x16x32_bf16 v[46:49], v[176:179], v[200:203], v[46:49]
	v_mfma_f32_16x16x32_bf16 v[18:21], v[168:171], v[208:211], v[18:21]
	v_mfma_f32_16x16x32_bf16 v[22:25], v[176:179], v[208:211], v[22:25]
	s_barrier
	s_cmp_gt_u32 s8, 29
	s_cbranch_scc1 .LBB0_350
	s_mov_b32 s8, s9
	s_branch .LBB0_346

.LBB0_625:
	s_add_u32 s13, s0, 0xfffc0080
	s_addc_u32 s14, s1, -1
	s_add_i32 s15, 0, 0x10000
	s_cmp_eq_u32 s12, 12
	s_cselect_b32 s39, s6, s14
	s_cselect_b32 s38, s7, s13
	v_add_u32_e32 v138, s15, v151
	s_cselect_b32 s35, s8, s11
	s_cselect_b32 s34, s9, s10
	s_add_i32 s13, 0, 0x14000
	ds_read_b128 v[164:167], v138
	ds_read_b128 v[168:171], v138 offset:1024
	ds_read_b128 v[172:175], v138 offset:2048
	ds_read_b128 v[176:179], v138 offset:3072
	v_add_u32_e32 v138, s13, v151
	ds_read_b128 v[180:183], v138
	ds_read_b128 v[184:187], v138 offset:1024
	ds_read_b128 v[188:191], v138 offset:2048
	ds_read_b128 v[192:195], v138 offset:3072
	v_lshl_add_u64 v[140:141], s[0:1], 0, v[154:155]
	s_add_i32 m0, s59, 0xc000
	ds_read_b128 v[196:199], v162
	ds_read_b128 v[200:203], v162 offset:1024
	ds_read_b128 v[204:207], v162 offset:2048
	ds_read_b128 v[208:211], v162 offset:3072
	ds_read_b128 v[212:215], v162 offset:4096
	ds_read_b128 v[216:219], v162 offset:5120
	ds_read_b128 v[236:239], v162 offset:6144
	ds_read_b128 v[240:243], v162 offset:7168
	global_load_lds_dwordx4 v[140:141], off
	v_lshl_add_u64 v[140:141], s[0:1], 0, v[156:157]
	s_add_i32 m0, s59, 0xe000
	s_nop 0
	global_load_lds_dwordx4 v[140:141], off
	s_waitcnt vmcnt(8)
	s_waitcnt lgkmcnt(0)
	s_barrier
	s_waitcnt lgkmcnt(0)
	v_mfma_f32_16x16x32_bf16 v[130:133], v[164:167], v[196:199], v[130:133]
	v_mfma_f32_16x16x32_bf16 v[126:129], v[172:175], v[196:199], v[126:129]
	v_mfma_f32_16x16x32_bf16 v[114:117], v[164:167], v[204:207], v[114:117]
	v_mfma_f32_16x16x32_bf16 v[110:113], v[172:175], v[204:207], v[110:113]
	v_mfma_f32_16x16x32_bf16 v[98:101], v[164:167], v[212:215], v[98:101]
	v_mfma_f32_16x16x32_bf16 v[94:97], v[172:175], v[212:215], v[94:97]
	v_mfma_f32_16x16x32_bf16 v[82:85], v[164:167], v[236:239], v[82:85]
	v_mfma_f32_16x16x32_bf16 v[78:81], v[172:175], v[236:239], v[78:81]
	v_mfma_f32_16x16x32_bf16 v[130:133], v[168:171], v[200:203], v[130:133]
	v_mfma_f32_16x16x32_bf16 v[126:129], v[176:179], v[200:203], v[126:129]
	v_mfma_f32_16x16x32_bf16 v[114:117], v[168:171], v[208:211], v[114:117]
	v_mfma_f32_16x16x32_bf16 v[110:113], v[176:179], v[208:211], v[110:113]
	v_mfma_f32_16x16x32_bf16 v[98:101], v[168:171], v[216:219], v[98:101]
	v_mfma_f32_16x16x32_bf16 v[94:97], v[176:179], v[216:219], v[94:97]
	v_mfma_f32_16x16x32_bf16 v[82:85], v[168:171], v[240:243], v[82:85]
	v_mfma_f32_16x16x32_bf16 v[78:81], v[176:179], v[240:243], v[78:81]
	v_mfma_f32_16x16x32_bf16 v[122:125], v[180:183], v[196:199], v[122:125]
	v_mfma_f32_16x16x32_bf16 v[118:121], v[188:191], v[196:199], v[118:121]
	v_mfma_f32_16x16x32_bf16 v[106:109], v[180:183], v[204:207], v[106:109]
	v_mfma_f32_16x16x32_bf16 v[102:105], v[188:191], v[204:207], v[102:105]
	v_mfma_f32_16x16x32_bf16 v[90:93], v[180:183], v[212:215], v[90:93]
	v_mfma_f32_16x16x32_bf16 v[86:89], v[188:191], v[212:215], v[86:89]
	v_mfma_f32_16x16x32_bf16 v[74:77], v[180:183], v[236:239], v[74:77]
	v_mfma_f32_16x16x32_bf16 v[70:73], v[188:191], v[236:239], v[70:73]
	v_mfma_f32_16x16x32_bf16 v[122:125], v[184:187], v[200:203], v[122:125]
	v_mfma_f32_16x16x32_bf16 v[118:121], v[192:195], v[200:203], v[118:121]
	v_mfma_f32_16x16x32_bf16 v[106:109], v[184:187], v[208:211], v[106:109]
	v_mfma_f32_16x16x32_bf16 v[102:105], v[192:195], v[208:211], v[102:105]
	v_mfma_f32_16x16x32_bf16 v[90:93], v[184:187], v[216:219], v[90:93]
	v_mfma_f32_16x16x32_bf16 v[86:89], v[192:195], v[216:219], v[86:89]
	v_mfma_f32_16x16x32_bf16 v[74:77], v[184:187], v[240:243], v[74:77]
	v_mfma_f32_16x16x32_bf16 v[70:73], v[192:195], v[240:243], v[70:73]
	s_barrier
	s_add_i32 s14, s15, s56
	v_lshl_add_u64 v[140:141], s[34:35], 0, v[146:147]
	s_mov_b32 m0, s14
	ds_read_b128 v[196:199], v162 offset:16384
	ds_read_b128 v[200:203], v162 offset:17408
	ds_read_b128 v[204:207], v162 offset:18432
	ds_read_b128 v[208:211], v162 offset:19456
	ds_read_b128 v[212:215], v162 offset:20480
	ds_read_b128 v[216:219], v162 offset:21504
	ds_read_b128 v[236:239], v162 offset:22528
	ds_read_b128 v[240:243], v162 offset:23552
	global_load_lds_dwordx4 v[140:141], off
	s_add_i32 m0, s14, 0x2000
	s_add_u32 s14, s34, 0x40000
	v_lshl_add_u64 v[142:143], s[34:35], 0, v[134:135]
	s_addc_u32 s15, s35, 0
	s_add_i32 s13, s13, s56
	global_load_lds_dwordx4 v[142:143], off
	v_lshl_add_u64 v[158:159], s[14:15], 0, v[146:147]
	s_mov_b32 m0, s13
	v_lshl_add_u64 v[220:221], s[38:39], 0, v[136:137]
	global_load_lds_dwordx4 v[158:159], off
	v_lshl_add_u64 v[158:159], s[14:15], 0, v[134:135]
	s_add_i32 m0, s13, 0x2000
	s_nop 0
	global_load_lds_dwordx4 v[158:159], off
	v_lshl_add_u64 v[158:159], s[38:39], 0, v[148:149]
	s_mov_b32 m0, s59
	s_nop 0
	global_load_lds_dwordx4 v[158:159], off
	s_mov_b32 m0, s60
	s_nop 0
	global_load_lds_dwordx4 v[220:221], off
	s_waitcnt vmcnt(8)
	s_waitcnt lgkmcnt(0)
	s_barrier
	s_waitcnt lgkmcnt(0)
	v_mfma_f32_16x16x32_bf16 v[66:69], v[164:167], v[196:199], v[66:69]
	v_mfma_f32_16x16x32_bf16 v[62:65], v[172:175], v[196:199], v[62:65]
	v_mfma_f32_16x16x32_bf16 v[50:53], v[164:167], v[204:207], v[50:53]
	v_mfma_f32_16x16x32_bf16 v[46:49], v[172:175], v[204:207], v[46:49]
	v_mfma_f32_16x16x32_bf16 v[34:37], v[164:167], v[212:215], v[34:37]
	v_mfma_f32_16x16x32_bf16 v[30:33], v[172:175], v[212:215], v[30:33]
	v_mfma_f32_16x16x32_bf16 v[18:21], v[164:167], v[236:239], v[18:21]
	v_mfma_f32_16x16x32_bf16 v[14:17], v[172:175], v[236:239], v[14:17]
	v_mfma_f32_16x16x32_bf16 v[66:69], v[168:171], v[200:203], v[66:69]
	v_mfma_f32_16x16x32_bf16 v[62:65], v[176:179], v[200:203], v[62:65]
	v_mfma_f32_16x16x32_bf16 v[50:53], v[168:171], v[208:211], v[50:53]
	v_mfma_f32_16x16x32_bf16 v[46:49], v[176:179], v[208:211], v[46:49]
	v_mfma_f32_16x16x32_bf16 v[34:37], v[168:171], v[216:219], v[34:37]
	v_mfma_f32_16x16x32_bf16 v[30:33], v[176:179], v[216:219], v[30:33]
	v_mfma_f32_16x16x32_bf16 v[18:21], v[168:171], v[240:243], v[18:21]
	v_mfma_f32_16x16x32_bf16 v[14:17], v[176:179], v[240:243], v[14:17]
	v_mfma_f32_16x16x32_bf16 v[58:61], v[180:183], v[196:199], v[58:61]
	v_mfma_f32_16x16x32_bf16 v[54:57], v[188:191], v[196:199], v[54:57]
	v_mfma_f32_16x16x32_bf16 v[42:45], v[180:183], v[204:207], v[42:45]
	v_mfma_f32_16x16x32_bf16 v[38:41], v[188:191], v[204:207], v[38:41]
	v_mfma_f32_16x16x32_bf16 v[26:29], v[180:183], v[212:215], v[26:29]
	v_mfma_f32_16x16x32_bf16 v[22:25], v[188:191], v[212:215], v[22:25]
	v_mfma_f32_16x16x32_bf16 v[10:13], v[180:183], v[236:239], v[10:13]
	v_mfma_f32_16x16x32_bf16 v[6:9], v[188:191], v[236:239], v[6:9]
	v_mfma_f32_16x16x32_bf16 v[58:61], v[184:187], v[200:203], v[58:61]
	v_mfma_f32_16x16x32_bf16 v[54:57], v[192:195], v[200:203], v[54:57]
	v_mfma_f32_16x16x32_bf16 v[42:45], v[184:187], v[208:211], v[42:45]
	v_mfma_f32_16x16x32_bf16 v[38:41], v[192:195], v[208:211], v[38:41]
	v_mfma_f32_16x16x32_bf16 v[26:29], v[184:187], v[216:219], v[26:29]
	v_mfma_f32_16x16x32_bf16 v[22:25], v[192:195], v[216:219], v[22:25]
	v_mfma_f32_16x16x32_bf16 v[10:13], v[184:187], v[240:243], v[10:13]
	v_mfma_f32_16x16x32_bf16 v[6:9], v[192:195], v[240:243], v[6:9]
	s_barrier
	s_add_i32 s13, 0, 0x18000
	v_add_u32_e32 v138, s13, v151
	s_add_i32 s16, 0, 0x1c000
	ds_read_b128 v[164:167], v138
	ds_read_b128 v[168:171], v138 offset:1024
	ds_read_b128 v[172:175], v138 offset:2048
	ds_read_b128 v[176:179], v138 offset:3072
	v_add_u32_e32 v138, s16, v151
	ds_read_b128 v[180:183], v138
	ds_read_b128 v[184:187], v138 offset:1024
	ds_read_b128 v[188:191], v138 offset:2048
	ds_read_b128 v[192:195], v138 offset:3072
	s_add_u32 s14, s38, 0x40000
	s_addc_u32 s15, s39, 0
	s_mov_b32 m0, s61
	v_lshl_add_u64 v[244:245], s[14:15], 0, v[148:149]
	ds_read_b128 v[196:199], v162 offset:32768
	ds_read_b128 v[200:203], v162 offset:33792
	ds_read_b128 v[204:207], v162 offset:34816
	ds_read_b128 v[208:211], v162 offset:35840
	ds_read_b128 v[212:215], v162 offset:36864
	ds_read_b128 v[216:219], v162 offset:37888
	ds_read_b128 v[236:239], v162 offset:38912
	ds_read_b128 v[240:243], v162 offset:39936
	global_load_lds_dwordx4 v[244:245], off
	v_lshl_add_u64 v[244:245], s[14:15], 0, v[136:137]
	s_mov_b32 m0, s62
	s_nop 0
	global_load_lds_dwordx4 v[244:245], off
	s_waitcnt vmcnt(8)
	s_waitcnt lgkmcnt(0)
	s_barrier
	s_waitcnt lgkmcnt(0)
	v_mfma_f32_16x16x32_bf16 v[130:133], v[164:167], v[196:199], v[130:133]
	v_mfma_f32_16x16x32_bf16 v[126:129], v[172:175], v[196:199], v[126:129]
	v_mfma_f32_16x16x32_bf16 v[114:117], v[164:167], v[204:207], v[114:117]
	v_mfma_f32_16x16x32_bf16 v[110:113], v[172:175], v[204:207], v[110:113]
	v_mfma_f32_16x16x32_bf16 v[98:101], v[164:167], v[212:215], v[98:101]
	v_mfma_f32_16x16x32_bf16 v[94:97], v[172:175], v[212:215], v[94:97]
	v_mfma_f32_16x16x32_bf16 v[82:85], v[164:167], v[236:239], v[82:85]
	v_mfma_f32_16x16x32_bf16 v[78:81], v[172:175], v[236:239], v[78:81]
	v_mfma_f32_16x16x32_bf16 v[130:133], v[168:171], v[200:203], v[130:133]
	v_mfma_f32_16x16x32_bf16 v[126:129], v[176:179], v[200:203], v[126:129]
	v_mfma_f32_16x16x32_bf16 v[114:117], v[168:171], v[208:211], v[114:117]
	v_mfma_f32_16x16x32_bf16 v[110:113], v[176:179], v[208:211], v[110:113]
	v_mfma_f32_16x16x32_bf16 v[98:101], v[168:171], v[216:219], v[98:101]
	v_mfma_f32_16x16x32_bf16 v[94:97], v[176:179], v[216:219], v[94:97]
	v_mfma_f32_16x16x32_bf16 v[82:85], v[168:171], v[240:243], v[82:85]
	v_mfma_f32_16x16x32_bf16 v[78:81], v[176:179], v[240:243], v[78:81]
	v_mfma_f32_16x16x32_bf16 v[122:125], v[180:183], v[196:199], v[122:125]
	v_mfma_f32_16x16x32_bf16 v[118:121], v[188:191], v[196:199], v[118:121]
	v_mfma_f32_16x16x32_bf16 v[106:109], v[180:183], v[204:207], v[106:109]
	v_mfma_f32_16x16x32_bf16 v[102:105], v[188:191], v[204:207], v[102:105]
	v_mfma_f32_16x16x32_bf16 v[90:93], v[180:183], v[212:215], v[90:93]
	v_mfma_f32_16x16x32_bf16 v[86:89], v[188:191], v[212:215], v[86:89]
	v_mfma_f32_16x16x32_bf16 v[74:77], v[180:183], v[236:239], v[74:77]
	v_mfma_f32_16x16x32_bf16 v[70:73], v[188:191], v[236:239], v[70:73]
	v_mfma_f32_16x16x32_bf16 v[122:125], v[184:187], v[200:203], v[122:125]
	v_mfma_f32_16x16x32_bf16 v[118:121], v[192:195], v[200:203], v[118:121]
	v_mfma_f32_16x16x32_bf16 v[106:109], v[184:187], v[208:211], v[106:109]
	v_mfma_f32_16x16x32_bf16 v[102:105], v[192:195], v[208:211], v[102:105]
	v_mfma_f32_16x16x32_bf16 v[90:93], v[184:187], v[216:219], v[90:93]
	v_mfma_f32_16x16x32_bf16 v[86:89], v[192:195], v[216:219], v[86:89]
	v_mfma_f32_16x16x32_bf16 v[74:77], v[184:187], v[240:243], v[74:77]
	v_mfma_f32_16x16x32_bf16 v[70:73], v[192:195], v[240:243], v[70:73]
	s_barrier
	s_add_i32 s13, s13, s56
	v_lshl_add_u64 v[140:141], v[140:141], 0, s[40:41]
	s_mov_b32 m0, s13
	ds_read_b128 v[196:199], v162 offset:49152
	ds_read_b128 v[200:203], v162 offset:50176
	ds_read_b128 v[204:207], v162 offset:51200
	ds_read_b128 v[208:211], v162 offset:52224
	ds_read_b128 v[212:215], v162 offset:53248
	ds_read_b128 v[216:219], v162 offset:54272
	ds_read_b128 v[236:239], v162 offset:55296
	ds_read_b128 v[240:243], v162 offset:56320
	global_load_lds_dwordx4 v[140:141], off
	s_add_i32 m0, s13, 0x2000
	s_add_u32 s14, s34, 0x40080
	v_lshl_add_u64 v[140:141], v[142:143], 0, s[40:41]
	s_addc_u32 s15, s35, 0
	s_add_i32 s13, s16, s56
	global_load_lds_dwordx4 v[140:141], off
	v_lshl_add_u64 v[140:141], s[14:15], 0, v[146:147]
	s_mov_b32 m0, s13
	s_nop 0
	global_load_lds_dwordx4 v[140:141], off
	v_lshl_add_u64 v[140:141], s[14:15], 0, v[134:135]
	s_add_i32 m0, s13, 0x2000
	s_nop 0
	global_load_lds_dwordx4 v[140:141], off
	v_lshl_add_u64 v[140:141], v[158:159], 0, s[40:41]
	s_mov_b32 m0, s64
	s_nop 0
	global_load_lds_dwordx4 v[140:141], off
	v_lshl_add_u64 v[140:141], v[220:221], 0, s[40:41]
	s_mov_b32 m0, s65
	s_nop 0
	global_load_lds_dwordx4 v[140:141], off
	s_waitcnt vmcnt(8)
	s_waitcnt lgkmcnt(0)
	s_barrier
	s_waitcnt lgkmcnt(0)
	v_mfma_f32_16x16x32_bf16 v[66:69], v[164:167], v[196:199], v[66:69]
	v_mfma_f32_16x16x32_bf16 v[62:65], v[172:175], v[196:199], v[62:65]
	v_mfma_f32_16x16x32_bf16 v[50:53], v[164:167], v[204:207], v[50:53]
	v_mfma_f32_16x16x32_bf16 v[46:49], v[172:175], v[204:207], v[46:49]
	v_mfma_f32_16x16x32_bf16 v[34:37], v[164:167], v[212:215], v[34:37]
	v_mfma_f32_16x16x32_bf16 v[30:33], v[172:175], v[212:215], v[30:33]
	v_mfma_f32_16x16x32_bf16 v[18:21], v[164:167], v[236:239], v[18:21]
	v_mfma_f32_16x16x32_bf16 v[14:17], v[172:175], v[236:239], v[14:17]
	v_mfma_f32_16x16x32_bf16 v[66:69], v[168:171], v[200:203], v[66:69]
	v_mfma_f32_16x16x32_bf16 v[62:65], v[176:179], v[200:203], v[62:65]
	v_mfma_f32_16x16x32_bf16 v[50:53], v[168:171], v[208:211], v[50:53]
	v_mfma_f32_16x16x32_bf16 v[46:49], v[176:179], v[208:211], v[46:49]
	v_mfma_f32_16x16x32_bf16 v[34:37], v[168:171], v[216:219], v[34:37]
	v_mfma_f32_16x16x32_bf16 v[30:33], v[176:179], v[216:219], v[30:33]
	v_mfma_f32_16x16x32_bf16 v[18:21], v[168:171], v[240:243], v[18:21]
	v_mfma_f32_16x16x32_bf16 v[14:17], v[176:179], v[240:243], v[14:17]
	v_mfma_f32_16x16x32_bf16 v[58:61], v[180:183], v[196:199], v[58:61]
	v_mfma_f32_16x16x32_bf16 v[54:57], v[188:191], v[196:199], v[54:57]
	v_mfma_f32_16x16x32_bf16 v[42:45], v[180:183], v[204:207], v[42:45]
	v_mfma_f32_16x16x32_bf16 v[38:41], v[188:191], v[204:207], v[38:41]
	v_mfma_f32_16x16x32_bf16 v[26:29], v[180:183], v[212:215], v[26:29]
	v_mfma_f32_16x16x32_bf16 v[22:25], v[188:191], v[212:215], v[22:25]
	v_mfma_f32_16x16x32_bf16 v[10:13], v[180:183], v[236:239], v[10:13]
	v_mfma_f32_16x16x32_bf16 v[6:9], v[188:191], v[236:239], v[6:9]
	v_mfma_f32_16x16x32_bf16 v[58:61], v[184:187], v[200:203], v[58:61]
	v_mfma_f32_16x16x32_bf16 v[54:57], v[192:195], v[200:203], v[54:57]
	v_mfma_f32_16x16x32_bf16 v[42:45], v[184:187], v[208:211], v[42:45]
	v_mfma_f32_16x16x32_bf16 v[38:41], v[192:195], v[208:211], v[38:41]
	v_mfma_f32_16x16x32_bf16 v[26:29], v[184:187], v[216:219], v[26:29]
	v_mfma_f32_16x16x32_bf16 v[22:25], v[192:195], v[216:219], v[22:25]
	v_mfma_f32_16x16x32_bf16 v[10:13], v[184:187], v[240:243], v[10:13]
	v_mfma_f32_16x16x32_bf16 v[6:9], v[192:195], v[240:243], v[6:9]
	s_barrier
	s_add_i32 s12, s12, 2
	s_add_u32 s0, s0, 0x100
	s_addc_u32 s1, s1, 0
	s_add_u32 s10, s10, 0x100
	s_addc_u32 s11, s11, 0
	s_cmp_gt_u32 s12, 13
	s_cbranch_scc0 .LBB0_625
	s_and_b64 vcc, exec, s[24:25]
	s_cbranch_vccz .LBB0_628
	s_barrier
